# GEMM epilogue stores made write-through (sc1) so the barrier write-back finds a clean L2; on top of early write-back v081
# baseline (speedup 1.0000x reference)
; #define LDA(dst, b, h) for (int m = 0; m < 4; ++m) for (int k = 0; k < 2; ++k) \
;     dst[m][k] = *reinterpret_cast<const bf16x8*>(SA(b, h) + lds_byte(wr * 64 + m * 16 + fr, k * 32 + fq * 8))
; #define LDB(dst, b, h) for (int n = 0; n < 2; ++n) for (int k = 0; k < 2; ++k) \
;     dst[n][k] = *reinterpret_cast<const bf16x8*>(SB(b, h) + lds_byte(wc * 32 + n * 16 + fr, k * 32 + fq * 8))
; #define MMA(ai, bj, At_, Bt_) do { __builtin_amdgcn_s_setprio(1); \
;     for (int m = 0; m < 4; ++m) for (int n = 0; n < 2; ++n) for (int k = 0; k < 2; ++k) \
;       acc[ai][bj][m][n] = __builtin_amdgcn_mfma_f32_16x16x32_bf16(Bt_[n][k], At_[m][k], acc[ai][bj][m][n], 0, 0, 0); \
;     __builtin_amdgcn_s_setprio(0); } while (0)
; #define WAIT_V(n) asm volatile("s_waitcnt vmcnt(" #n ")" ::: "memory")
; #define WAIT_L(n) asm volatile("s_waitcnt lgkmcnt(" #n ")" ::: "memory")
; #define BAR __builtin_amdgcn_s_barrier()
; #define SCHED __builtin_amdgcn_sched_barrier(0)
; #define STG(P, PTR, LD, O0) do { const bf16_t* _g = (PTR); \
;     __builtin_amdgcn_global_load_lds((const unsigned*)(_g + O0), (lds_u32*)((P) + swave * 1024), 16, 0, 0); \
;     __builtin_amdgcn_global_load_lds((const unsigned*)(_g + (size_t)64 * (LD) + O0), (lds_u32*)((P) + swave * 1024 + 8192), 16, 0, 0); } while (0)
; #define LDA(dst, b, h) for (int m = 0; m < 4; ++m) for (int k = 0; k < 2; ++k) \
;     dst[m][k] = *reinterpret_cast<const bf16x8*>(SA(b, h) + lds_byte(wr * 64 + m * 16 + fr, k * 32 + fq * 8))
; #define WAIT_V(n) asm volatile("s_waitcnt vmcnt(" #n ")" ::: "memory")
; __device__ __forceinline__ void gemm_stream(int swave, const GemmJob& J, char* shm, int vb, int G) {
;     ...
;     for (int t = 0; t < nt; t += 2) {
;       const bool last = (t == nt - 2);
;       const bf16_t* xA = last ? nA : cA; const bf16_t* xA1 = last ? nA1 : cA1; const int k2 = last ? 0 : t + 2;
;       const bf16_t* b2 = last ? nB : cB + (size_t)(t + 2) * 64; const bf16_t* b3 = b2 + 64;
;       LDB(B0, 0, 0); SCHED; LDA(At, 0, 0); STGA(SA(1, 1), cA, cA1, t + 1, 1);
;       WAIT_L(8); BAR; WAIT_L(0); MMA(0, 0, At, B0); BAR; SCHED;
;       LDB(B1, 0, 1); STG(SB(0, 0), b2, ldb, offB0);
;       BAR; WAIT_L(0); MMA(0, 1, At, B1); BAR;
;       LDA(At, 0, 1); STGA(SA(0, 0), xA, xA1, k2, 0);
;       BAR; WAIT_L(0); MMA(1, 0, At, B0); BAR; SCHED;
;       STG(SB(0, 1), b2 + hB, ldb, offB0);
;       WAIT_V(6); BAR; MMA(1, 1, At, B1); BAR;
.LBB0_729:
	ds_read_b128 v[164:167], v139
	ds_read_b128 v[168:171], v139 offset:1024
	ds_read_b128 v[172:175], v139 offset:2048
	ds_read_b128 v[176:179], v139 offset:3072
	s_cmp_eq_u32 s49, s29
	s_cselect_b64 s[68:69], -1, 0
	s_and_b64 s[64:65], s[68:69], exec
	s_cselect_b32 s52, s10, s8
	s_cselect_b32 s64, s11, s9
	s_add_i32 s33, s2, 2
	s_and_b64 s[68:69], s[68:69], exec
	s_cselect_b32 s71, s15, s21
	s_cselect_b32 s70, s14, s20
	s_cselect_b32 s68, 0, s33
	s_cselect_b32 s65, s12, s16
	s_cselect_b32 s66, s13, s17
	s_or_b32 s2, s2, 1
	s_cmp_lt_u32 s2, s36
	s_cselect_b64 vcc, -1, 0
	s_and_b64 s[2:3], vcc, exec
	s_cselect_b32 s3, 0, s36
	s_cselect_b32 s2, s38, s37
	s_not_b32 s3, s3
	s_add_i32 s94, s3, s29
	s_and_b64 s[72:73], vcc, exec
	s_cselect_b32 s3, s9, s17
	s_cselect_b32 s69, s8, s16
	s_lshl_b64 s[72:73], s[94:95], 7
	s_add_u32 s69, s69, s72
	s_addc_u32 s74, s3, s73
	s_mov_b32 s3, s95
	s_lshl_b64 s[72:73], s[2:3], 8
	s_add_u32 s72, s69, s72
	v_cndmask_b32_e32 v2, v138, v0, vcc
	s_addc_u32 s73, s74, s73
	s_add_i32 m0, s42, 0xc000
	s_lshl_b64 s[2:3], s[2:3], 7
	v_lshlrev_b64 v[212:213], 1, v[2:3]
	s_add_u32 s2, s72, s2
	v_lshl_add_u64 v[214:215], s[72:73], 0, v[212:213]
	s_addc_u32 s3, s73, s3
	ds_read_b128 v[180:183], v144
	ds_read_b128 v[188:191], v145
	ds_read_b128 v[196:199], v159
	ds_read_b128 v[204:207], v160
	global_load_lds_dwordx4 v[214:215], off
	v_lshl_add_u64 v[212:213], s[2:3], 0, v[212:213]
	s_add_i32 m0, s42, 0xe000
	s_nop 0
	global_load_lds_dwordx4 v[212:213], off
	s_waitcnt lgkmcnt(4)
	s_barrier
	s_waitcnt lgkmcnt(0)
	v_mfma_f32_16x16x32_bf16 v[128:131], v[164:167], v[180:183], v[128:131]
	ds_read_b128 v[184:187], v144 offset:1024
	v_mfma_f32_16x16x32_bf16 v[124:127], v[172:175], v[180:183], v[124:127]
	ds_read_b128 v[192:195], v145 offset:1024
	v_mfma_f32_16x16x32_bf16 v[120:123], v[164:167], v[188:191], v[120:123]
	ds_read_b128 v[200:203], v159 offset:1024
	v_mfma_f32_16x16x32_bf16 v[116:119], v[172:175], v[188:191], v[116:119]
	ds_read_b128 v[208:211], v160 offset:1024
	v_mfma_f32_16x16x32_bf16 v[104:107], v[164:167], v[196:199], v[104:107]
	v_mfma_f32_16x16x32_bf16 v[100:103], v[172:175], v[196:199], v[100:103]
	v_mfma_f32_16x16x32_bf16 v[88:91], v[164:167], v[204:207], v[88:91]
	v_mfma_f32_16x16x32_bf16 v[84:87], v[172:175], v[204:207], v[84:87]
	s_waitcnt lgkmcnt(0)
	v_mfma_f32_16x16x32_bf16 v[128:131], v[168:171], v[184:187], v[128:131]
	v_mfma_f32_16x16x32_bf16 v[124:127], v[176:179], v[184:187], v[124:127]
	v_mfma_f32_16x16x32_bf16 v[120:123], v[168:171], v[192:195], v[120:123]
	v_mfma_f32_16x16x32_bf16 v[116:119], v[176:179], v[192:195], v[116:119]
	v_mfma_f32_16x16x32_bf16 v[104:107], v[168:171], v[200:203], v[104:107]
	v_mfma_f32_16x16x32_bf16 v[100:103], v[176:179], v[200:203], v[100:103]
	v_mfma_f32_16x16x32_bf16 v[88:91], v[168:171], v[208:211], v[88:91]
	v_mfma_f32_16x16x32_bf16 v[84:87], v[176:179], v[208:211], v[84:87]
	s_barrier
	s_add_u32 s2, s70, s0
	s_mov_b32 m0, s43
	v_lshl_add_u64 v[228:229], s[70:71], 0, v[136:137]
	s_addc_u32 s3, s71, s1
	ds_read_b128 v[212:215], v161
	ds_read_b128 v[216:219], v161 offset:1024
	ds_read_b128 v[220:223], v161 offset:2048
	ds_read_b128 v[224:227], v161 offset:3072
	global_load_lds_dwordx4 v[228:229], off
	v_lshl_add_u64 v[230:231], s[2:3], 0, v[136:137]
	s_mov_b32 m0, s44
	s_nop 0
	global_load_lds_dwordx4 v[230:231], off
	s_barrier
	s_waitcnt lgkmcnt(0)
	v_mfma_f32_16x16x32_bf16 v[112:115], v[212:215], v[180:183], v[112:115]
	v_mfma_f32_16x16x32_bf16 v[108:111], v[220:223], v[180:183], v[108:111]
	s_cmp_lt_u32 s68, s36
	s_cselect_b64 vcc, -1, 0
	v_mfma_f32_16x16x32_bf16 v[96:99], v[212:215], v[188:191], v[96:99]
	s_and_b64 s[70:71], vcc, exec
	s_cselect_b32 s70, s38, s37
	v_mfma_f32_16x16x32_bf16 v[92:95], v[220:223], v[188:191], v[92:95]
	s_sub_i32 s69, s68, s36
	s_min_u32 s94, s68, s69
	v_mfma_f32_16x16x32_bf16 v[80:83], v[212:215], v[196:199], v[80:83]
	s_and_b64 s[72:73], vcc, exec
	s_cselect_b32 s69, s64, s66
	v_mfma_f32_16x16x32_bf16 v[76:79], v[220:223], v[196:199], v[76:79]
	s_cselect_b32 s71, s52, s65
	s_lshl_b64 s[72:73], s[94:95], 7
	v_mfma_f32_16x16x32_bf16 v[72:75], v[212:215], v[204:207], v[72:75]
	v_cndmask_b32_e32 v2, v138, v0, vcc
	s_add_u32 s72, s71, s72
	v_mfma_f32_16x16x32_bf16 v[68:71], v[220:223], v[204:207], v[68:71]
	s_mov_b32 s71, s95
	v_mfma_f32_16x16x32_bf16 v[112:115], v[216:219], v[184:187], v[112:115]
	s_addc_u32 s73, s69, s73
	v_mfma_f32_16x16x32_bf16 v[108:111], v[224:227], v[184:187], v[108:111]
	v_lshlrev_b64 v[232:233], 1, v[2:3]
	v_mfma_f32_16x16x32_bf16 v[96:99], v[216:219], v[192:195], v[96:99]
	s_lshl_b64 s[70:71], s[70:71], 7
	v_mfma_f32_16x16x32_bf16 v[92:95], v[224:227], v[192:195], v[92:95]
	v_lshl_add_u64 v[234:235], s[72:73], 0, v[232:233]
	v_mfma_f32_16x16x32_bf16 v[80:83], v[216:219], v[200:203], v[80:83]
	s_add_u32 s72, s72, s70
	v_mfma_f32_16x16x32_bf16 v[76:79], v[224:227], v[200:203], v[76:79]
	s_mov_b32 m0, s42
	v_mfma_f32_16x16x32_bf16 v[72:75], v[216:219], v[208:211], v[72:75]
	s_addc_u32 s73, s73, s71
	v_mfma_f32_16x16x32_bf16 v[68:71], v[224:227], v[208:211], v[68:71]
	s_barrier
	ds_read_b128 v[180:183], v144 offset:16384
	ds_read_b128 v[188:191], v145 offset:16384
	ds_read_b128 v[196:199], v159 offset:16384
	ds_read_b128 v[204:207], v160 offset:16384
	global_load_lds_dwordx4 v[234:235], off
	v_lshl_add_u64 v[234:235], s[72:73], 0, v[232:233]
	s_mov_b32 m0, s39
	s_nop 0
	global_load_lds_dwordx4 v[234:235], off
	s_barrier
; #define LDA(dst, b, h) for (int m = 0; m < 4; ++m) for (int k = 0; k < 2; ++k) \
;     dst[m][k] = *reinterpret_cast<const bf16x8*>(SA(b, h) + lds_byte(wr * 64 + m * 16 + fr, k * 32 + fq * 8))
; #define LDB(dst, b, h) for (int n = 0; n < 2; ++n) for (int k = 0; k < 2; ++k) \
;     dst[n][k] = *reinterpret_cast<const bf16x8*>(SB(b, h) + lds_byte(wc * 32 + n * 16 + fr, k * 32 + fq * 8))
; #define MMA(ai, bj, At_, Bt_) do { __builtin_amdgcn_s_setprio(1); \
;     for (int m = 0; m < 4; ++m) for (int n = 0; n < 2; ++n) for (int k = 0; k < 2; ++k) \
;       acc[ai][bj][m][n] = __builtin_amdgcn_mfma_f32_16x16x32_bf16(Bt_[n][k], At_[m][k], acc[ai][bj][m][n], 0, 0, 0); \
;     __builtin_amdgcn_s_setprio(0); } while (0)
; #define WAIT_V(n) asm volatile("s_waitcnt vmcnt(" #n ")" ::: "memory")
; #define WAIT_L(n) asm volatile("s_waitcnt lgkmcnt(" #n ")" ::: "memory")
; #define BAR __builtin_amdgcn_s_barrier()
; #define SCHED __builtin_amdgcn_sched_barrier(0)
; #define STG(P, PTR, LD, O0) do { const bf16_t* _g = (PTR); \
;     __builtin_amdgcn_global_load_lds((const unsigned*)(_g + O0), (lds_u32*)((P) + swave * 1024), 16, 0, 0); \
;     __builtin_amdgcn_global_load_lds((const unsigned*)(_g + (size_t)64 * (LD) + O0), (lds_u32*)((P) + swave * 1024 + 8192), 16, 0, 0); } while (0)
; #define LDA(dst, b, h) for (int m = 0; m < 4; ++m) for (int k = 0; k < 2; ++k) \
;     dst[m][k] = *reinterpret_cast<const bf16x8*>(SA(b, h) + lds_byte(wr * 64 + m * 16 + fr, k * 32 + fq * 8))
; #define LDB(dst, b, h) for (int n = 0; n < 2; ++n) for (int k = 0; k < 2; ++k) \
;     dst[n][k] = *reinterpret_cast<const bf16x8*>(SB(b, h) + lds_byte(wc * 32 + n * 16 + fr, k * 32 + fq * 8))
; #define WAIT_V(n) asm volatile("s_waitcnt vmcnt(" #n ")" ::: "memory")
; __device__ __forceinline__ void gemm_stream(int swave, const GemmJob& J, char* shm, int vb, int G) {
;     ...
;       LDA(At, 0, 1); STGA(SA(0, 0), xA, xA1, k2, 0);
;       BAR; WAIT_L(0); MMA(1, 0, At, B0); BAR; SCHED;
;       STG(SB(0, 1), b2 + hB, ldb, offB0);
;       WAIT_V(6); BAR; MMA(1, 1, At, B1); BAR;
;       LDB(B0, 1, 0); SCHED; LDA(At, 1, 0); STGA(SA(0, 1), xA, xA1, k2, 1);
;       WAIT_L(8); BAR; WAIT_L(0); MMA(0, 0, At, B0); BAR; SCHED;
;       LDB(B1, 1, 1); STG(SB(1, 0), b3, ldb, offB0);
;       BAR; WAIT_L(0); MMA(0, 1, At, B1); BAR;
;       LDA(At, 1, 1); STGA(SA(1, 0), xA, xA1, k2 + 1, 0);
	s_waitcnt lgkmcnt(0)
	v_mfma_f32_16x16x32_bf16 v[64:67], v[164:167], v[180:183], v[64:67]
	ds_read_b128 v[184:187], v144 offset:17408
	v_mfma_f32_16x16x32_bf16 v[60:63], v[172:175], v[180:183], v[60:63]
	ds_read_b128 v[192:195], v145 offset:17408
	v_mfma_f32_16x16x32_bf16 v[56:59], v[164:167], v[188:191], v[56:59]
	ds_read_b128 v[200:203], v159 offset:17408
	v_mfma_f32_16x16x32_bf16 v[52:55], v[172:175], v[188:191], v[52:55]
	ds_read_b128 v[208:211], v160 offset:17408
	v_mfma_f32_16x16x32_bf16 v[40:43], v[164:167], v[196:199], v[40:43]
	v_mfma_f32_16x16x32_bf16 v[36:39], v[172:175], v[196:199], v[36:39]
	v_mfma_f32_16x16x32_bf16 v[24:27], v[164:167], v[204:207], v[24:27]
	v_mfma_f32_16x16x32_bf16 v[20:23], v[172:175], v[204:207], v[20:23]
	s_waitcnt lgkmcnt(0)
	v_mfma_f32_16x16x32_bf16 v[64:67], v[168:171], v[184:187], v[64:67]
	v_mfma_f32_16x16x32_bf16 v[60:63], v[176:179], v[184:187], v[60:63]
	v_mfma_f32_16x16x32_bf16 v[56:59], v[168:171], v[192:195], v[56:59]
	v_mfma_f32_16x16x32_bf16 v[52:55], v[176:179], v[192:195], v[52:55]
	v_mfma_f32_16x16x32_bf16 v[40:43], v[168:171], v[200:203], v[40:43]
	v_mfma_f32_16x16x32_bf16 v[36:39], v[176:179], v[200:203], v[36:39]
	v_mfma_f32_16x16x32_bf16 v[24:27], v[168:171], v[208:211], v[24:27]
	v_mfma_f32_16x16x32_bf16 v[20:23], v[176:179], v[208:211], v[20:23]
	s_barrier
	s_add_u32 s2, s2, s0
	s_addc_u32 s3, s3, s1
	v_lshl_add_u64 v[234:235], s[2:3], 0, v[136:137]
	s_add_u32 s2, s2, s0
	s_mov_b32 m0, s45
	s_addc_u32 s3, s3, s1
	global_load_lds_dwordx4 v[234:235], off
	v_lshl_add_u64 v[236:237], s[2:3], 0, v[136:137]
	s_mov_b32 m0, s46
	s_nop 0
	global_load_lds_dwordx4 v[236:237], off
	s_waitcnt vmcnt(6)
	s_barrier
	v_mfma_f32_16x16x32_bf16 v[48:51], v[212:215], v[180:183], v[48:51]
	v_mfma_f32_16x16x32_bf16 v[44:47], v[220:223], v[180:183], v[44:47]
	v_mfma_f32_16x16x32_bf16 v[32:35], v[212:215], v[188:191], v[32:35]
	v_mfma_f32_16x16x32_bf16 v[28:31], v[220:223], v[188:191], v[28:31]
	v_mfma_f32_16x16x32_bf16 v[16:19], v[212:215], v[196:199], v[16:19]
	v_mfma_f32_16x16x32_bf16 v[12:15], v[220:223], v[196:199], v[12:15]
	v_mfma_f32_16x16x32_bf16 v[8:11], v[212:215], v[204:207], v[8:11]
	v_mfma_f32_16x16x32_bf16 v[4:7], v[220:223], v[204:207], v[4:7]
	v_mfma_f32_16x16x32_bf16 v[48:51], v[216:219], v[184:187], v[48:51]
	v_mfma_f32_16x16x32_bf16 v[44:47], v[224:227], v[184:187], v[44:47]
	v_mfma_f32_16x16x32_bf16 v[32:35], v[216:219], v[192:195], v[32:35]
	v_mfma_f32_16x16x32_bf16 v[28:31], v[224:227], v[192:195], v[28:31]
	v_mfma_f32_16x16x32_bf16 v[16:19], v[216:219], v[200:203], v[16:19]
	v_mfma_f32_16x16x32_bf16 v[12:15], v[224:227], v[200:203], v[12:15]
	v_mfma_f32_16x16x32_bf16 v[8:11], v[216:219], v[208:211], v[8:11]
	v_mfma_f32_16x16x32_bf16 v[4:7], v[224:227], v[208:211], v[4:7]
	s_barrier
	ds_read_b128 v[164:167], v162
	ds_read_b128 v[168:171], v162 offset:1024
	ds_read_b128 v[172:175], v162 offset:2048
	ds_read_b128 v[176:179], v162 offset:3072
	s_add_u32 s2, s72, s70
	s_addc_u32 s3, s73, s71
	v_lshl_add_u64 v[212:213], s[2:3], 0, v[232:233]
	s_add_u32 s2, s2, s70
	s_mov_b32 m0, s47
	s_addc_u32 s3, s3, s71
	ds_read_b128 v[180:183], v144 offset:32768
	ds_read_b128 v[188:191], v145 offset:32768
	ds_read_b128 v[196:199], v159 offset:32768
	ds_read_b128 v[204:207], v160 offset:32768
	global_load_lds_dwordx4 v[212:213], off
	v_lshl_add_u64 v[212:213], s[2:3], 0, v[232:233]
	s_mov_b32 m0, s48
	s_nop 0
	global_load_lds_dwordx4 v[212:213], off
	s_waitcnt lgkmcnt(4)
	s_barrier
	s_waitcnt lgkmcnt(0)
	v_mfma_f32_16x16x32_bf16 v[128:131], v[164:167], v[180:183], v[128:131]
	ds_read_b128 v[184:187], v144 offset:33792
	v_mfma_f32_16x16x32_bf16 v[124:127], v[172:175], v[180:183], v[124:127]
	ds_read_b128 v[192:195], v145 offset:33792
	v_mfma_f32_16x16x32_bf16 v[120:123], v[164:167], v[188:191], v[120:123]
	ds_read_b128 v[200:203], v159 offset:33792
	v_mfma_f32_16x16x32_bf16 v[116:119], v[172:175], v[188:191], v[116:119]
	ds_read_b128 v[208:211], v160 offset:33792
	v_mfma_f32_16x16x32_bf16 v[104:107], v[164:167], v[196:199], v[104:107]
	v_mfma_f32_16x16x32_bf16 v[100:103], v[172:175], v[196:199], v[100:103]
	v_mfma_f32_16x16x32_bf16 v[88:91], v[164:167], v[204:207], v[88:91]
	v_mfma_f32_16x16x32_bf16 v[84:87], v[172:175], v[204:207], v[84:87]
	s_waitcnt lgkmcnt(0)
	v_mfma_f32_16x16x32_bf16 v[128:131], v[168:171], v[184:187], v[128:131]
	v_mfma_f32_16x16x32_bf16 v[124:127], v[176:179], v[184:187], v[124:127]
	v_mfma_f32_16x16x32_bf16 v[120:123], v[168:171], v[192:195], v[120:123]
	v_mfma_f32_16x16x32_bf16 v[116:119], v[176:179], v[192:195], v[116:119]
	v_mfma_f32_16x16x32_bf16 v[104:107], v[168:171], v[200:203], v[104:107]
	v_mfma_f32_16x16x32_bf16 v[100:103], v[176:179], v[200:203], v[100:103]
	v_mfma_f32_16x16x32_bf16 v[88:91], v[168:171], v[208:211], v[88:91]
	v_mfma_f32_16x16x32_bf16 v[84:87], v[176:179], v[208:211], v[84:87]
	s_barrier
	v_lshl_add_u64 v[228:229], v[228:229], 0, s[22:23]
	s_add_i32 m0, s42, 0x18000
	ds_read_b128 v[212:215], v163
	ds_read_b128 v[216:219], v163 offset:1024
	ds_read_b128 v[220:223], v163 offset:2048
	ds_read_b128 v[224:227], v163 offset:3072
	global_load_lds_dwordx4 v[228:229], off
	v_lshl_add_u64 v[228:229], v[230:231], 0, s[22:23]
	s_add_i32 m0, s42, 0x1a000
	s_nop 0
	global_load_lds_dwordx4 v[228:229], off
	s_barrier
; #define LDA(dst, b, h) for (int m = 0; m < 4; ++m) for (int k = 0; k < 2; ++k) \
;     dst[m][k] = *reinterpret_cast<const bf16x8*>(SA(b, h) + lds_byte(wr * 64 + m * 16 + fr, k * 32 + fq * 8))
; #define MMA(ai, bj, At_, Bt_) do { __builtin_amdgcn_s_setprio(1); \
;     for (int m = 0; m < 4; ++m) for (int n = 0; n < 2; ++n) for (int k = 0; k < 2; ++k) \
;       acc[ai][bj][m][n] = __builtin_amdgcn_mfma_f32_16x16x32_bf16(Bt_[n][k], At_[m][k], acc[ai][bj][m][n], 0, 0, 0); \
;     __builtin_amdgcn_s_setprio(0); } while (0)
; #define WAIT_V(n) asm volatile("s_waitcnt vmcnt(" #n ")" ::: "memory")
; #define WAIT_L(n) asm volatile("s_waitcnt lgkmcnt(" #n ")" ::: "memory")
; #define BAR __builtin_amdgcn_s_barrier()
; #define SCHED __builtin_amdgcn_sched_barrier(0)
; #define STG(P, PTR, LD, O0) do { const bf16_t* _g = (PTR); \
;     __builtin_amdgcn_global_load_lds((const unsigned*)(_g + O0), (lds_u32*)((P) + swave * 1024), 16, 0, 0); \
;     __builtin_amdgcn_global_load_lds((const unsigned*)(_g + (size_t)64 * (LD) + O0), (lds_u32*)((P) + swave * 1024 + 8192), 16, 0, 0); } while (0)
; #define LDA(dst, b, h) for (int m = 0; m < 4; ++m) for (int k = 0; k < 2; ++k) \
;     dst[m][k] = *reinterpret_cast<const bf16x8*>(SA(b, h) + lds_byte(wr * 64 + m * 16 + fr, k * 32 + fq * 8))
; #define MMA(ai, bj, At_, Bt_) do { __builtin_amdgcn_s_setprio(1); \
;     for (int m = 0; m < 4; ++m) for (int n = 0; n < 2; ++n) for (int k = 0; k < 2; ++k) \
;       acc[ai][bj][m][n] = __builtin_amdgcn_mfma_f32_16x16x32_bf16(Bt_[n][k], At_[m][k], acc[ai][bj][m][n], 0, 0, 0); \
;     __builtin_amdgcn_s_setprio(0); } while (0)
; #define WAIT_V(n) asm volatile("s_waitcnt vmcnt(" #n ")" ::: "memory")
; #define WAIT_L(n) asm volatile("s_waitcnt lgkmcnt(" #n ")" ::: "memory")
; #define BAR __builtin_amdgcn_s_barrier()
; #define SCHED __builtin_amdgcn_sched_barrier(0)
; __device__ __forceinline__ void gemm_stream(int swave, const GemmJob& J, char* shm, int vb, int G) {
;     ...
;       BAR; WAIT_L(0); MMA(0, 1, At, B1); BAR;
;       LDA(At, 1, 1); STGA(SA(1, 0), xA, xA1, k2 + 1, 0);
;       BAR; WAIT_L(0); MMA(1, 0, At, B0); BAR; SCHED;
;       STG(SB(1, 1), b3 + hB, ldb, offB0);
;       WAIT_V(6); BAR; MMA(1, 1, At, B1); BAR;
;     }
	s_waitcnt lgkmcnt(0)
	v_mfma_f32_16x16x32_bf16 v[112:115], v[212:215], v[180:183], v[112:115]
	v_mfma_f32_16x16x32_bf16 v[108:111], v[220:223], v[180:183], v[108:111]
	s_or_b32 s68, s68, 1
	s_cmp_lt_u32 s68, s36
	v_mfma_f32_16x16x32_bf16 v[96:99], v[212:215], v[188:191], v[96:99]
	s_cselect_b64 vcc, -1, 0
	s_and_b64 s[2:3], vcc, exec
	v_mfma_f32_16x16x32_bf16 v[92:95], v[220:223], v[188:191], v[92:95]
	s_cselect_b32 s69, s38, s37
	s_sub_i32 s2, s68, s36
	v_mfma_f32_16x16x32_bf16 v[80:83], v[212:215], v[196:199], v[80:83]
	s_min_u32 s94, s68, s2
	s_and_b64 s[2:3], vcc, exec
	v_mfma_f32_16x16x32_bf16 v[76:79], v[220:223], v[196:199], v[76:79]
	s_cselect_b32 s64, s64, s66
	s_cselect_b32 s52, s52, s65
	v_mfma_f32_16x16x32_bf16 v[72:75], v[212:215], v[204:207], v[72:75]
	s_lshl_b64 s[2:3], s[94:95], 7
	v_cndmask_b32_e32 v2, v138, v0, vcc
	v_mfma_f32_16x16x32_bf16 v[68:71], v[220:223], v[204:207], v[68:71]
	s_add_u32 s2, s52, s2
	v_mfma_f32_16x16x32_bf16 v[112:115], v[216:219], v[184:187], v[112:115]
	s_addc_u32 s3, s64, s3
	v_mfma_f32_16x16x32_bf16 v[108:111], v[224:227], v[184:187], v[108:111]
	v_lshlrev_b64 v[228:229], 1, v[2:3]
	v_mfma_f32_16x16x32_bf16 v[96:99], v[216:219], v[192:195], v[96:99]
	s_lshl_b32 s52, s69, 7
	v_mfma_f32_16x16x32_bf16 v[92:95], v[224:227], v[192:195], v[92:95]
	v_lshl_add_u64 v[230:231], s[2:3], 0, v[228:229]
	v_mfma_f32_16x16x32_bf16 v[80:83], v[216:219], v[200:203], v[80:83]
	s_add_u32 s2, s2, s52
	v_mfma_f32_16x16x32_bf16 v[76:79], v[224:227], v[200:203], v[76:79]
	s_mov_b32 m0, s54
	v_mfma_f32_16x16x32_bf16 v[72:75], v[216:219], v[208:211], v[72:75]
	s_addc_u32 s3, s3, 0
	v_mfma_f32_16x16x32_bf16 v[68:71], v[224:227], v[208:211], v[68:71]
	s_barrier
	ds_read_b128 v[180:183], v144 offset:49152
	ds_read_b128 v[188:191], v145 offset:49152
	ds_read_b128 v[196:199], v159 offset:49152
	ds_read_b128 v[204:207], v160 offset:49152
	global_load_lds_dwordx4 v[230:231], off
	v_lshl_add_u64 v[228:229], s[2:3], 0, v[228:229]
	s_mov_b32 m0, s55
	s_nop 0
	global_load_lds_dwordx4 v[228:229], off
	s_barrier
	s_waitcnt lgkmcnt(0)
	v_mfma_f32_16x16x32_bf16 v[64:67], v[164:167], v[180:183], v[64:67]
	ds_read_b128 v[184:187], v144 offset:50176
	v_mfma_f32_16x16x32_bf16 v[60:63], v[172:175], v[180:183], v[60:63]
	ds_read_b128 v[192:195], v145 offset:50176
	v_mfma_f32_16x16x32_bf16 v[56:59], v[164:167], v[188:191], v[56:59]
	ds_read_b128 v[200:203], v159 offset:50176
	v_mfma_f32_16x16x32_bf16 v[52:55], v[172:175], v[188:191], v[52:55]
	ds_read_b128 v[208:211], v160 offset:50176
	v_mfma_f32_16x16x32_bf16 v[40:43], v[164:167], v[196:199], v[40:43]
	v_mfma_f32_16x16x32_bf16 v[36:39], v[172:175], v[196:199], v[36:39]
	v_mfma_f32_16x16x32_bf16 v[24:27], v[164:167], v[204:207], v[24:27]
	v_mfma_f32_16x16x32_bf16 v[20:23], v[172:175], v[204:207], v[20:23]
	s_waitcnt lgkmcnt(0)
	v_mfma_f32_16x16x32_bf16 v[64:67], v[168:171], v[184:187], v[64:67]
	v_mfma_f32_16x16x32_bf16 v[60:63], v[176:179], v[184:187], v[60:63]
	v_mfma_f32_16x16x32_bf16 v[56:59], v[168:171], v[192:195], v[56:59]
	v_mfma_f32_16x16x32_bf16 v[52:55], v[176:179], v[192:195], v[52:55]
	v_mfma_f32_16x16x32_bf16 v[40:43], v[168:171], v[200:203], v[40:43]
	v_mfma_f32_16x16x32_bf16 v[36:39], v[176:179], v[200:203], v[36:39]
	v_mfma_f32_16x16x32_bf16 v[24:27], v[168:171], v[208:211], v[24:27]
	v_mfma_f32_16x16x32_bf16 v[20:23], v[176:179], v[208:211], v[20:23]
	s_barrier
	v_lshl_add_u64 v[164:165], v[234:235], 0, s[22:23]
	s_add_i32 m0, s42, 0x1c000
	s_nop 0
	global_load_lds_dwordx4 v[164:165], off
	v_lshl_add_u64 v[164:165], v[236:237], 0, s[22:23]
	s_add_i32 m0, s42, 0x1e000
	s_nop 0
	global_load_lds_dwordx4 v[164:165], off
	s_waitcnt vmcnt(6)
	s_barrier
	v_mfma_f32_16x16x32_bf16 v[48:51], v[212:215], v[180:183], v[48:51]
	v_mfma_f32_16x16x32_bf16 v[44:47], v[220:223], v[180:183], v[44:47]
	s_add_i32 s29, s29, 2
	v_mfma_f32_16x16x32_bf16 v[32:35], v[212:215], v[188:191], v[32:35]
	s_add_u32 s20, s20, 0x100
	v_mfma_f32_16x16x32_bf16 v[28:31], v[220:223], v[188:191], v[28:31]
	s_addc_u32 s21, s21, 0
	v_mfma_f32_16x16x32_bf16 v[16:19], v[212:215], v[196:199], v[16:19]
	s_cmp_ge_u32 s33, s49
	v_mfma_f32_16x16x32_bf16 v[12:15], v[220:223], v[196:199], v[12:15]
	s_mov_b32 s2, s33
	v_mfma_f32_16x16x32_bf16 v[8:11], v[212:215], v[204:207], v[8:11]
	v_mfma_f32_16x16x32_bf16 v[4:7], v[220:223], v[204:207], v[4:7]
	v_mfma_f32_16x16x32_bf16 v[48:51], v[216:219], v[184:187], v[48:51]
	v_mfma_f32_16x16x32_bf16 v[44:47], v[224:227], v[184:187], v[44:47]
	v_mfma_f32_16x16x32_bf16 v[32:35], v[216:219], v[192:195], v[32:35]
	v_mfma_f32_16x16x32_bf16 v[28:31], v[224:227], v[192:195], v[28:31]
	v_mfma_f32_16x16x32_bf16 v[16:19], v[216:219], v[200:203], v[16:19]
	v_mfma_f32_16x16x32_bf16 v[12:15], v[224:227], v[200:203], v[12:15]
	v_mfma_f32_16x16x32_bf16 v[8:11], v[216:219], v[208:211], v[8:11]
	v_mfma_f32_16x16x32_bf16 v[4:7], v[224:227], v[208:211], v[4:7]
	s_barrier
; __device__ __forceinline__ unsigned pk2(float lo, float hi) { f32x2_t v = {lo, hi}; bf16x2_t b = __builtin_convertvector(v, bf16x2_t); return __builtin_bit_cast(unsigned, b); }
; __device__ __forceinline__ void gemm_stream(int swave, const GemmJob& J, char* shm, int vb, int G) {
;     ...
;     {
;       bf16_t* C = (bf16_t*)((char*)J.c0 + (size_t)cg * J.strideC);
; #pragma unroll
;       for (int ai = 0; ai < 2; ++ai)
; #pragma unroll
;         for (int m = 0; m < 4; ++m)
; #pragma unroll
;           for (int bj = 0; bj < 2; ++bj) {
;             const f32x4 v0 = acc[ai][bj][m][0], v1 = acc[ai][bj][m][1];
;             uint4 o; o.x = pk2(v0[0], v0[1]); o.y = pk2(v0[2], v0[3]); o.z = pk2(v1[0], v1[1]); o.w = pk2(v1[2], v1[3]);
;             *(uint4*)(C + (size_t)(cbrow + ai * 128 + wr * 64 + m * 16 + fr) * J.ldc + cbcol + bj * 128 + wc * 32 + fq * 8) = o;
;           }
;     }
;     if (!has_next) break;
; #pragma unroll
;     for (int a_ = 0; a_ < 2; ++a_)
; #pragma unroll
;       for (int b_ = 0; b_ < 2; ++b_)
; #pragma unroll
;         for (int m = 0; m < 4; ++m)
; #pragma unroll
;           for (int n = 0; n < 2; ++n) acc[a_][b_][m][n] = (f32x4){0.f, 0.f, 0.f, 0.f};
;     id = nid; cg = ng; cbrow = nbrow; cbcol = nbcol; cA = nA; cA1 = nA1; cB = nB;
;   }
	s_cbranch_scc0 .LBB0_729
	v_add_u32_e32 v164, s5, v1
	s_ashr_i32 s5, s4, 31
	s_lshl_b64 s[2:3], s[4:5], 1
	v_ashrrev_i32_e32 v2, 31, v164
	s_add_u32 s2, s50, s2
	v_cvt_pk_bf16_f32 v128, v128, v129
	v_cvt_pk_bf16_f32 v129, v130, v131
	v_cvt_pk_bf16_f32 v130, v124, v125
	v_mul_lo_u32 v2, v2, s18
	v_mad_u64_u32 v[124:125], s[4:5], v164, s18, 0
	s_addc_u32 s3, s51, s3
	v_add_u32_e32 v125, v125, v2
	v_lshl_add_u64 v[124:125], v[124:125], 1, s[2:3]
	v_mov_b32_e32 v141, v3
	v_lshl_add_u64 v[124:125], v[124:125], 0, v[140:141]
	v_mov_b32_e32 v143, v3
	v_lshl_add_u64 v[124:125], v[124:125], 0, v[142:143]
	s_lshl_b32 s2, s18, 5
	s_mov_b32 s3, 0
	s_mul_i32 s4, s18, 0xa0
	s_mov_b32 s5, 0
	v_cvt_pk_bf16_f32 v112, v112, v113
	v_cvt_pk_bf16_f32 v113, v114, v115
	v_cvt_pk_bf16_f32 v114, v108, v109
	v_cvt_pk_bf16_f32 v115, v110, v111
	global_store_dwordx4 v[124:125], v[112:115], off offset:256 sc1
	v_cvt_pk_bf16_f32 v131, v126, v127
	v_cvt_pk_bf16_f32 v96, v96, v97
	v_lshl_add_u64 v[112:113], v[124:125], 0, s[2:3]
	v_cvt_pk_bf16_f32 v97, v98, v99
	v_cvt_pk_bf16_f32 v98, v92, v93
	v_cvt_pk_bf16_f32 v99, v94, v95
	global_store_dwordx4 v[124:125], v[128:131], off sc1
	global_store_dwordx4 v[112:113], v[96:99], off offset:256 sc1
	v_cvt_pk_bf16_f32 v108, v120, v121
	v_cvt_pk_bf16_f32 v109, v122, v123
	v_lshl_add_u64 v[96:97], v[112:113], 0, s[2:3]
	v_cvt_pk_bf16_f32 v110, v116, v117
	v_cvt_pk_bf16_f32 v111, v118, v119
	v_cvt_pk_bf16_f32 v80, v80, v81
	v_cvt_pk_bf16_f32 v81, v82, v83
	v_cvt_pk_bf16_f32 v82, v76, v77
	v_cvt_pk_bf16_f32 v83, v78, v79
	global_store_dwordx4 v[112:113], v[108:111], off sc1
	global_store_dwordx4 v[96:97], v[80:83], off offset:256 sc1
	v_cvt_pk_bf16_f32 v64, v64, v65
	v_cvt_pk_bf16_f32 v65, v66, v67
	v_lshl_add_u64 v[80:81], v[96:97], 0, s[2:3]
	v_cvt_pk_bf16_f32 v66, v60, v61
	v_lshl_add_u64 v[60:61], v[80:81], 0, s[4:5]
	v_cvt_pk_bf16_f32 v72, v72, v73
	v_cvt_pk_bf16_f32 v73, v74, v75
	v_cvt_pk_bf16_f32 v74, v68, v69
	v_cvt_pk_bf16_f32 v67, v62, v63
	v_cvt_pk_bf16_f32 v92, v104, v105
	v_cvt_pk_bf16_f32 v93, v106, v107
	v_cvt_pk_bf16_f32 v94, v100, v101
	v_cvt_pk_bf16_f32 v95, v102, v103
	v_cvt_pk_bf16_f32 v76, v88, v89
	v_cvt_pk_bf16_f32 v77, v90, v91
	v_cvt_pk_bf16_f32 v78, v84, v85
	v_cvt_pk_bf16_f32 v79, v86, v87
	v_cvt_pk_bf16_f32 v75, v70, v71
	v_cvt_pk_bf16_f32 v48, v48, v49
	v_cvt_pk_bf16_f32 v49, v50, v51
	v_cvt_pk_bf16_f32 v50, v44, v45
	v_cvt_pk_bf16_f32 v51, v46, v47
	global_store_dwordx4 v[96:97], v[92:95], off sc1
	global_store_dwordx4 v[80:81], v[76:79], off sc1
	global_store_dwordx4 v[80:81], v[72:75], off offset:256 sc1
	global_store_dwordx4 v[60:61], v[48:51], off offset:256 sc1
	v_cvt_pk_bf16_f32 v32, v32, v33
	v_cvt_pk_bf16_f32 v33, v34, v35
	v_lshl_add_u64 v[48:49], v[60:61], 0, s[2:3]
	v_cvt_pk_bf16_f32 v34, v28, v29
	v_cvt_pk_bf16_f32 v35, v30, v31
	global_store_dwordx4 v[60:61], v[64:67], off sc1
	global_store_dwordx4 v[48:49], v[32:35], off offset:256 sc1
	v_cvt_pk_bf16_f32 v44, v56, v57
	v_cvt_pk_bf16_f32 v45, v58, v59
	v_lshl_add_u64 v[32:33], v[48:49], 0, s[2:3]
	v_cvt_pk_bf16_f32 v46, v52, v53
	v_cvt_pk_bf16_f32 v47, v54, v55
	v_cvt_pk_bf16_f32 v16, v16, v17
	v_cvt_pk_bf16_f32 v17, v18, v19
	v_cvt_pk_bf16_f32 v18, v12, v13
	v_cvt_pk_bf16_f32 v19, v14, v15
	global_store_dwordx4 v[48:49], v[44:47], off sc1
	global_store_dwordx4 v[32:33], v[16:19], off offset:256 sc1
	v_cvt_pk_bf16_f32 v28, v40, v41
	v_cvt_pk_bf16_f32 v29, v42, v43
	v_lshl_add_u64 v[16:17], v[32:33], 0, s[2:3]
	v_cvt_pk_bf16_f32 v30, v36, v37
	v_cvt_pk_bf16_f32 v31, v38, v39
	v_cvt_pk_bf16_f32 v12, v24, v25
	v_cvt_pk_bf16_f32 v13, v26, v27
	v_cvt_pk_bf16_f32 v14, v20, v21
	v_cvt_pk_bf16_f32 v15, v22, v23
	v_cvt_pk_bf16_f32 v8, v8, v9
	v_cvt_pk_bf16_f32 v9, v10, v11
	v_cvt_pk_bf16_f32 v10, v4, v5
	v_cvt_pk_bf16_f32 v11, v6, v7
	s_and_b64 vcc, exec, s[6:7]
	s_mov_b64 s[2:3], s[14:15]
	s_mov_b64 s[16:17], s[12:13]
	s_mov_b64 s[8:9], s[10:11]
	s_mov_b32 s4, s56
	s_mov_b32 s5, s28
	global_store_dwordx4 v[32:33], v[28:31], off sc1
	global_store_dwordx4 v[16:17], v[12:15], off sc1
	global_store_dwordx4 v[16:17], v[8:11], off offset:256 sc1
	s_cbranch_vccz .LBB0_726
	s_waitcnt vmcnt(0)
	s_movk_i32 s66, 0x100
	v_cmp_gt_u32_e32 vcc, s66, v135
	s_and_saveexec_b64 s[0:1], vcc
	s_cbranch_execz .LBB0_733
	s_barrier
